# tile-order lever: GEMM M-grouping WGM 8->4 in the three EpiResid phases (P2, P12, P15) so one XCD round covers whole 2048-column row panels (both StaticOrder decode sites), on top of v13
# speedup vs baseline: 1.0147x; 1.0147x over previous
; #define INP(k) ((const float*)PTR(k))
; #define WSP(off) (PTR(29) + (off))
;     __device__ bool next(int i, Unit& u) const {
;         const long L = (long)i * G + c; if (L >= nwg) return false;
;         int wgid = (int)L; { const int q = nwg / NXCD, r = nwg % NXCD, xcd = wgid % NXCD, off = wgid / NXCD; wgid = (xcd < r ? xcd * (q + 1) : r * (q + 1) + (xcd - r) * q) + off; }
;         const int nig = WGM * nN, gid = wgid / nig, fm = gid * WGM, gsz = (nM - fm) < WGM ? (nM - fm) : WGM;
;         u.pm = fm + ((wgid % nig) % gsz); u.pn = (wgid % nig) / gsz; return true;
;     }
; template <int K>
; __device__ __forceinline__ void run_phase(LAS unsigned char* lds, volatile LAS unsigned* ptab) {
;     ...
;         pg8::Gemm g{(const bf16_t*)WSP(WS_BIG), (const bf16_t*)WSP(WS_WAD), MROWS, DM, DFF, DFF}; pg8::StaticOrder S; S.init(MROWS, DM, G, bx);
;         pg8::EpiResid E{INP(0), INP(1), OUTP, DM, 0.5f, (bf16_t*)WSP(WS_XN), INP(6), (float*)WSP(WS_SS1)};
.LBB0_294:
	s_add_i32 s0, 0, 0x230ec
	v_mov_b32_e32 v0, s0
	ds_read_b32 v1, v0
	s_add_i32 s0, 0, 0x230e8
	v_mov_b32_e32 v2, s0
	ds_read_b32 v3, v2
	ds_read_b32 v4, v0
	s_add_i32 s0, 0, 0x23004
	s_waitcnt lgkmcnt(2)
	v_readfirstlane_b32 s12, v1
	ds_read_b32 v1, v2
	v_mov_b32_e32 v5, s0
	s_add_i32 s0, 0, 0x23000
	v_mov_b32_e32 v6, s0
	s_add_i32 s0, 0, 0x2300c
	s_waitcnt lgkmcnt(0)
	v_readfirstlane_b32 s20, v1
	v_mov_b32_e32 v1, s0
	s_add_i32 s0, 0, 0x23008
	ds_read_b32 v5, v5
	v_readfirstlane_b32 s15, v3
	v_mov_b32_e32 v3, s0
	s_add_i32 s0, 0, 0x230e4
	ds_read_b32 v6, v6
	v_readfirstlane_b32 s13, v4
	ds_read_b32 v1, v1
	ds_read_b32 v3, v3
	v_mov_b32_e32 v4, s0
	ds_read_b32 v4, v4
	s_add_i32 s0, 0, 0x230e0
	s_waitcnt lgkmcnt(4)
	v_readfirstlane_b32 s2, v5
	v_mov_b32_e32 v5, s0
	s_add_i32 s0, 0, 0x23034
	s_waitcnt lgkmcnt(1)
	v_readfirstlane_b32 s5, v3
	v_mov_b32_e32 v3, s0
	s_add_i32 s0, 0, 0x23030
	s_waitcnt lgkmcnt(0)
	v_readfirstlane_b32 s9, v4
	v_mov_b32_e32 v4, s0
	v_readfirstlane_b32 s33, v6
	ds_read_b32 v5, v5
	ds_read_b32 v6, v0
	v_readfirstlane_b32 s4, v1
	ds_read_b32 v1, v2
	ds_read_b32 v3, v3
	ds_read_b32 v4, v4
	ds_read_b32 v0, v0
	ds_read_b32 v2, v2
	v_mov_b32_e32 v8, v166
	s_cmpk_lt_i32 s3, 0x300
	s_waitcnt lgkmcnt(6)
	v_readfirstlane_b32 s8, v5
	s_waitcnt lgkmcnt(5)
	v_readfirstlane_b32 s7, v6
	s_waitcnt lgkmcnt(4)
	v_readfirstlane_b32 s14, v1
	s_waitcnt lgkmcnt(3)
	v_readfirstlane_b32 s11, v3
	s_waitcnt lgkmcnt(2)
	v_readfirstlane_b32 s10, v4
	s_waitcnt lgkmcnt(1)
	v_readfirstlane_b32 s19, v0
	s_waitcnt lgkmcnt(0)
	v_readfirstlane_b32 s18, v2
	s_cselect_b64 s[0:1], -1, 0
	s_cmpk_gt_i32 s3, 0x2ff
	v_readfirstlane_b32 s6, v8
	s_cbranch_scc1 .LBB0_296
	s_ashr_i32 s21, s3, 31
	s_lshr_b32 s21, s21, 29
	s_add_i32 s21, s3, s21
	s_ashr_i32 s22, s21, 3
	s_and_b32 s21, s21, -8
	s_sub_i32 s21, s3, s21
	s_cmp_lt_i32 s21, 0
	s_movk_i32 s23, 0x61
	s_cselect_b32 s23, s23, 0x60
	s_mul_i32 s21, s23, s21
	s_add_i32 s21, s21, s22
	s_lshr_b32 s22, s21, 5
	s_lshl_b32 s22, s22, 2
	s_and_b32 s23, s21, 3
	s_add_i32 s62, s22, s23
	s_bfe_u32 s61, s21, 0x30002

;     __device__ bool next(int i, Unit& u) const {
;         const long L = (long)i * G + c; if (L >= nwg) return false;
;         int wgid = (int)L; { const int q = nwg / NXCD, r = nwg % NXCD, xcd = wgid % NXCD, off = wgid / NXCD; wgid = (xcd < r ? xcd * (q + 1) : r * (q + 1) + (xcd - r) * q) + off; }
;         const int nig = WGM * nN, gid = wgid / nig, fm = gid * WGM, gsz = (nM - fm) < WGM ? (nM - fm) : WGM;
;         u.pm = fm + ((wgid % nig) % gsz); u.pn = (wgid % nig) / gsz; return true;
;     }
.LBB0_302:
	s_add_i32 s47, s47, 1
	s_mul_i32 s4, s47, s50
	s_mul_hi_u32 s5, s47, s51
	s_add_i32 s5, s5, s4
	s_mul_i32 s4, s47, s51
	s_add_u32 s6, s4, s3
	s_addc_u32 s7, s5, s52
	v_cmp_gt_i64_e32 vcc, s[6:7], v[154:155]
	v_cmp_lt_i64_e64 s[4:5], s[6:7], v[152:153]
	s_cbranch_vccnz .LBB0_304
	s_ashr_i32 s7, s6, 31
	s_lshr_b32 s7, s7, 29
	s_add_i32 s7, s6, s7
	s_ashr_i32 s26, s7, 3
	s_and_b32 s7, s7, -8
	s_sub_i32 s6, s6, s7
	s_cmp_lt_i32 s6, 0
	s_cselect_b32 s7, s55, 0x60
	s_mul_i32 s6, s7, s6
	s_add_i32 s6, s6, s26
	s_ashr_i32 s7, s6, 31
	s_lshr_b32 s7, s7, 27
	s_add_i32 s7, s6, s7
	s_ashr_i32 s26, s7, 5
	s_lshl_b32 s26, s26, 2
	s_sub_i32 s27, 0x60, s26
	s_min_i32 s27, s27, 4
	s_abs_i32 s28, s27
	v_cvt_f32_u32_e32 v0, s28
	s_sub_i32 s36, 0, s28
	s_andn2_b32 s7, s7, 31
	s_sub_i32 s6, s6, s7
	v_rcp_iflag_f32_e32 v0, v0
	s_abs_i32 s7, s6
	s_xor_b32 s29, s6, s27
	s_ashr_i32 s29, s29, 31
	v_mul_f32_e32 v0, 0x4f7ffffe, v0
	v_cvt_u32_f32_e32 v0, v0
	s_nop 0
	v_readfirstlane_b32 s37, v0
	s_mul_i32 s36, s36, s37
	s_mul_hi_u32 s36, s37, s36
	s_add_i32 s37, s37, s36
	s_mul_hi_u32 s36, s7, s37
	s_mul_i32 s37, s36, s28
	s_sub_i32 s7, s7, s37
	s_add_i32 s59, s36, 1
	s_sub_i32 s37, s7, s28
	s_cmp_ge_u32 s7, s28
	s_cselect_b32 s36, s59, s36
	s_cselect_b32 s7, s37, s7
	s_add_i32 s37, s36, 1
	s_cmp_ge_u32 s7, s28
	s_cselect_b32 s7, s37, s36
	s_xor_b32 s7, s7, s29
	s_sub_i32 s59, s7, s29
	s_mul_i32 s7, s59, s27
	s_sub_i32 s6, s6, s7
	s_add_i32 s60, s6, s26

; #define INP(k) ((const float*)PTR(k))
; #define WSP(off) (PTR(29) + (off))
;     __device__ bool next(int i, Unit& u) const {
;         const long L = (long)i * G + c; if (L >= nwg) return false;
;         int wgid = (int)L; { const int q = nwg / NXCD, r = nwg % NXCD, xcd = wgid % NXCD, off = wgid / NXCD; wgid = (xcd < r ? xcd * (q + 1) : r * (q + 1) + (xcd - r) * q) + off; }
;         const int nig = WGM * nN, gid = wgid / nig, fm = gid * WGM, gsz = (nM - fm) < WGM ? (nM - fm) : WGM;
;         u.pm = fm + ((wgid % nig) % gsz); u.pn = (wgid % nig) / gsz; return true;
;     }
; template <int K>
; __device__ __forceinline__ void run_phase(LAS unsigned char* lds, volatile LAS unsigned* ptab) {
;     ...
;     if constexpr (K == 12) {
;         float* out = OUTP;
;         pg8::Gemm g{(const bf16_t*)WSP(WS_XN), (const bf16_t*)WSP(WS_WOUT), MROWS, DM, DM, DM}; pg8::StaticOrder S; S.init(MROWS, DM, G, bx);
;         pg8::EpiResid E{out, out + (size_t)SEQ_P * DM, out, DM, 1.0f, (bf16_t*)WSP(WS_XN2), INP(23), (float*)WSP(WS_SS2)};
.LBB0_1071:
	s_or_b64 exec, exec, s[0:1]
	s_waitcnt lgkmcnt(0)
	v_mov_b32_e32 v0, v166
	s_barrier
	s_add_i32 s0, 0, 0x230e4
	v_mov_b32_e32 v0, s0
	s_add_i32 s0, 0, 0x230e0
	ds_read_b32 v0, v0
	v_mov_b32_e32 v1, s0
	ds_read_b32 v1, v1
	s_add_i32 s0, 0, 0x230ec
	v_readlane_b32 s16, v252, 14
	s_waitcnt lgkmcnt(1)
	v_readfirstlane_b32 s9, v0
	v_mov_b32_e32 v0, s0
	s_add_i32 s0, 0, 0x230e8
	s_waitcnt lgkmcnt(0)
	v_readfirstlane_b32 s8, v1
	ds_read_b32 v1, v0
	v_mov_b32_e32 v2, s0
	ds_read_b32 v3, v2
	ds_read_b32 v4, v0
	ds_read_b32 v5, v2
	ds_read_b32 v6, v0
	s_add_i32 s0, 0, 0x230bc
	s_waitcnt lgkmcnt(3)
	v_readfirstlane_b32 s2, v3
	v_mov_b32_e32 v3, s0
	s_add_i32 s0, 0, 0x230b8
	s_waitcnt lgkmcnt(2)
	v_readfirstlane_b32 s12, v4
	v_mov_b32_e32 v4, s0
	v_readfirstlane_b32 s5, v1
	ds_read_b32 v1, v2
	ds_read_b32 v3, v3
	ds_read_b32 v4, v4
	ds_read_b32 v0, v0
	ds_read_b32 v2, v2
	v_mov_b32_e32 v8, v166
	v_readlane_b32 s17, v252, 15
	s_waitcnt lgkmcnt(6)
	v_readfirstlane_b32 s13, v5
	s_waitcnt lgkmcnt(5)
	v_readfirstlane_b32 s1, v6
	s_waitcnt lgkmcnt(4)
	v_readfirstlane_b32 s14, v1
	s_waitcnt lgkmcnt(3)
	v_readfirstlane_b32 s11, v3
	s_waitcnt lgkmcnt(2)
	v_readfirstlane_b32 s10, v4
	s_waitcnt lgkmcnt(1)
	v_readfirstlane_b32 s6, v0
	s_waitcnt lgkmcnt(0)
	v_readfirstlane_b32 s7, v2
	s_and_b64 vcc, exec, s[16:17]
	v_readfirstlane_b32 s0, v8
	s_cbranch_vccnz .LBB0_1073
	s_ashr_i32 s4, s3, 31
	s_lshr_b32 s4, s4, 29
	s_add_i32 s4, s3, s4
	s_ashr_i32 s15, s4, 3
	s_and_b32 s4, s4, -8
	s_sub_i32 s4, s3, s4
	s_cmp_lt_i32 s4, 0
	s_movk_i32 s16, 0x61
	s_cselect_b32 s16, s16, 0x60
	s_mul_i32 s4, s16, s4
	s_add_i32 s4, s4, s15
	s_lshr_b32 s15, s4, 5
	s_lshl_b32 s15, s15, 2
	s_and_b32 s16, s4, 3
	s_add_i32 s34, s15, s16
	s_bfe_u32 s4, s4, 0x30002

;     __device__ bool next(int i, Unit& u) const {
;         const long L = (long)i * G + c; if (L >= nwg) return false;
;         int wgid = (int)L; { const int q = nwg / NXCD, r = nwg % NXCD, xcd = wgid % NXCD, off = wgid / NXCD; wgid = (xcd < r ? xcd * (q + 1) : r * (q + 1) + (xcd - r) * q) + off; }
;         const int nig = WGM * nN, gid = wgid / nig, fm = gid * WGM, gsz = (nM - fm) < WGM ? (nM - fm) : WGM;
;         u.pm = fm + ((wgid % nig) % gsz); u.pn = (wgid % nig) / gsz; return true;
;     }
.LBB0_1079:
	s_add_i32 s49, s49, 1
	s_mul_i32 s5, s49, s52
	s_mul_hi_u32 s6, s49, s53
	s_add_i32 s6, s6, s5
	s_mul_i32 s5, s49, s53
	s_add_u32 s28, s5, s3
	s_addc_u32 s29, s6, s54
	v_cmp_gt_i64_e32 vcc, s[28:29], v[154:155]
	v_cmp_lt_i64_e64 s[6:7], s[28:29], v[152:153]
	s_cbranch_vccnz .LBB0_1081
	s_ashr_i32 s5, s28, 31
	s_lshr_b32 s5, s5, 29
	s_add_i32 s5, s28, s5
	s_ashr_i32 s24, s5, 3
	s_and_b32 s5, s5, -8
	s_sub_i32 s5, s28, s5
	s_cmp_lt_i32 s5, 0
	s_cselect_b32 s25, s55, 0x60
	s_mul_i32 s5, s25, s5
	s_add_i32 s5, s5, s24
	s_ashr_i32 s24, s5, 31
	s_lshr_b32 s24, s24, 27
	s_add_i32 s24, s5, s24
	s_ashr_i32 s25, s24, 5
	s_lshl_b32 s25, s25, 2
	s_sub_i32 s26, 0x60, s25
	s_min_i32 s26, s26, 4
	s_abs_i32 s27, s26
	v_cvt_f32_u32_e32 v0, s27
	s_sub_i32 s29, 0, s27
	s_andn2_b32 s24, s24, 31
	s_sub_i32 s5, s5, s24
	v_rcp_iflag_f32_e32 v0, v0
	s_abs_i32 s24, s5
	s_xor_b32 s28, s5, s26
	s_ashr_i32 s28, s28, 31
	v_mul_f32_e32 v0, 0x4f7ffffe, v0
	v_cvt_u32_f32_e32 v0, v0
	s_nop 0
	v_readfirstlane_b32 s30, v0
	s_mul_i32 s29, s29, s30
	s_mul_hi_u32 s29, s30, s29
	s_add_i32 s30, s30, s29
	s_mul_hi_u32 s29, s24, s30
	s_mul_i32 s30, s29, s27
	s_sub_i32 s24, s24, s30
	s_add_i32 s31, s29, 1
	s_sub_i32 s30, s24, s27
	s_cmp_ge_u32 s24, s27
	s_cselect_b32 s29, s31, s29
	s_cselect_b32 s24, s30, s24
	s_add_i32 s30, s29, 1
	s_cmp_ge_u32 s24, s27
	s_cselect_b32 s24, s30, s29
	s_xor_b32 s24, s24, s28
	s_sub_i32 s24, s24, s28
	s_mul_i32 s26, s24, s26
	s_sub_i32 s5, s5, s26
	s_add_i32 s26, s5, s25

; #define INP(k) ((const float*)PTR(k))
; #define WSP(off) (PTR(29) + (off))
;     __device__ bool next(int i, Unit& u) const {
;         const long L = (long)i * G + c; if (L >= nwg) return false;
;         int wgid = (int)L; { const int q = nwg / NXCD, r = nwg % NXCD, xcd = wgid % NXCD, off = wgid / NXCD; wgid = (xcd < r ? xcd * (q + 1) : r * (q + 1) + (xcd - r) * q) + off; }
;         const int nig = WGM * nN, gid = wgid / nig, fm = gid * WGM, gsz = (nM - fm) < WGM ? (nM - fm) : WGM;
;         u.pm = fm + ((wgid % nig) % gsz); u.pn = (wgid % nig) / gsz; return true;
;     }
; template <int K>
; __device__ __forceinline__ void run_phase(LAS unsigned char* lds, volatile LAS unsigned* ptab) {
;     ...
;     if constexpr (K == 15) {
;         float* out = OUTP;
;         pg8::Gemm g{(const bf16_t*)WSP(WS_H2), (const bf16_t*)WSP(WS_WAD2), MROWS, DM, DFF, DFF}; pg8::StaticOrder S; S.init(MROWS, DM, G, bx);
;         pg8::EpiResid E{out, out + (size_t)SEQ_P * DM, nullptr, DM, 0.5f, (bf16_t*)WSP(WS_XN2), INP(27), (float*)WSP(WS_SS3)};
.LBB0_1364:
	s_or_b64 exec, exec, s[0:1]
	s_waitcnt lgkmcnt(0)
	v_mov_b32_e32 v0, v166
	s_barrier
	s_add_i32 s0, 0, 0x230e4
	v_mov_b32_e32 v0, s0
	s_add_i32 s0, 0, 0x230e0
	ds_read_b32 v0, v0
	v_mov_b32_e32 v1, s0
	ds_read_b32 v1, v1
	s_add_i32 s0, 0, 0x230ec
	v_readlane_b32 s16, v252, 14
	s_waitcnt lgkmcnt(1)
	v_readfirstlane_b32 s9, v0
	v_mov_b32_e32 v0, s0
	s_add_i32 s0, 0, 0x230e8
	s_waitcnt lgkmcnt(0)
	v_readfirstlane_b32 s8, v1
	ds_read_b32 v1, v0
	v_mov_b32_e32 v2, s0
	ds_read_b32 v3, v2
	ds_read_b32 v4, v0
	ds_read_b32 v5, v2
	ds_read_b32 v6, v0
	s_add_i32 s0, 0, 0x230dc
	s_waitcnt lgkmcnt(3)
	v_readfirstlane_b32 s2, v3
	v_mov_b32_e32 v3, s0
	s_add_i32 s0, 0, 0x230d8
	s_waitcnt lgkmcnt(2)
	v_readfirstlane_b32 s6, v4
	v_mov_b32_e32 v4, s0
	v_readfirstlane_b32 s4, v1
	ds_read_b32 v1, v2
	ds_read_b32 v3, v3
	ds_read_b32 v4, v4
	ds_read_b32 v0, v0
	ds_read_b32 v2, v2
	v_mov_b32_e32 v8, v166
	v_readlane_b32 s17, v252, 15
	s_waitcnt lgkmcnt(6)
	v_readfirstlane_b32 s12, v5
	s_waitcnt lgkmcnt(5)
	v_readfirstlane_b32 s1, v6
	s_waitcnt lgkmcnt(4)
	v_readfirstlane_b32 s14, v1
	s_waitcnt lgkmcnt(3)
	v_readfirstlane_b32 s11, v3
	s_waitcnt lgkmcnt(2)
	v_readfirstlane_b32 s10, v4
	s_waitcnt lgkmcnt(1)
	v_readfirstlane_b32 s5, v0
	s_waitcnt lgkmcnt(0)
	v_readfirstlane_b32 s7, v2
	s_and_b64 vcc, exec, s[16:17]
	v_readfirstlane_b32 s0, v8
	s_cbranch_vccnz .LBB0_1366
	s_ashr_i32 s13, s3, 31
	s_lshr_b32 s13, s13, 29
	s_add_i32 s13, s3, s13
	s_ashr_i32 s15, s13, 3
	s_and_b32 s13, s13, -8
	s_sub_i32 s13, s3, s13
	s_cmp_lt_i32 s13, 0
	s_movk_i32 s16, 0x61
	s_cselect_b32 s16, s16, 0x60
	s_mul_i32 s13, s16, s13
	s_add_i32 s13, s13, s15
	s_lshr_b32 s15, s13, 5
	s_lshl_b32 s15, s15, 2
	s_and_b32 s16, s13, 3
	s_add_i32 s54, s15, s16
	s_bfe_u32 s53, s13, 0x30002

;     __device__ bool next(int i, Unit& u) const {
;         const long L = (long)i * G + c; if (L >= nwg) return false;
;         int wgid = (int)L; { const int q = nwg / NXCD, r = nwg % NXCD, xcd = wgid % NXCD, off = wgid / NXCD; wgid = (xcd < r ? xcd * (q + 1) : r * (q + 1) + (xcd - r) * q) + off; }
;         const int nig = WGM * nN, gid = wgid / nig, fm = gid * WGM, gsz = (nM - fm) < WGM ? (nM - fm) : WGM;
;         u.pm = fm + ((wgid % nig) % gsz); u.pn = (wgid % nig) / gsz; return true;
;     }
.LBB0_1372:
	s_add_i32 s41, s41, 1
	s_mul_i32 s4, s41, s44
	s_mul_hi_u32 s5, s41, s45
	s_add_i32 s5, s5, s4
	s_mul_i32 s4, s41, s45
	s_add_u32 s6, s4, s3
	s_addc_u32 s7, s5, s46
	v_cmp_gt_i64_e32 vcc, s[6:7], v[154:155]
	v_cmp_lt_i64_e64 s[4:5], s[6:7], v[152:153]
	s_cbranch_vccnz .LBB0_1374
	s_ashr_i32 s7, s6, 31
	s_lshr_b32 s7, s7, 29
	s_add_i32 s7, s6, s7
	s_ashr_i32 s22, s7, 3
	s_and_b32 s7, s7, -8
	s_sub_i32 s6, s6, s7
	s_cmp_lt_i32 s6, 0
	s_cselect_b32 s7, s47, 0x60
	s_mul_i32 s6, s7, s6
	s_add_i32 s6, s6, s22
	s_ashr_i32 s7, s6, 31
	s_lshr_b32 s7, s7, 27
	s_add_i32 s7, s6, s7
	s_ashr_i32 s22, s7, 5
	s_lshl_b32 s22, s22, 2
	s_sub_i32 s23, 0x60, s22
	s_min_i32 s23, s23, 4
	s_abs_i32 s28, s23
	v_cvt_f32_u32_e32 v0, s28
	s_sub_i32 s30, 0, s28
	s_andn2_b32 s7, s7, 31
	s_sub_i32 s6, s6, s7
	v_rcp_iflag_f32_e32 v0, v0
	s_abs_i32 s7, s6
	s_xor_b32 s29, s6, s23
	s_ashr_i32 s29, s29, 31
	v_mul_f32_e32 v0, 0x4f7ffffe, v0
	v_cvt_u32_f32_e32 v0, v0
	s_nop 0
	v_readfirstlane_b32 s31, v0
	s_mul_i32 s30, s30, s31
	s_mul_hi_u32 s30, s31, s30
	s_add_i32 s31, s31, s30
	s_mul_hi_u32 s30, s7, s31
	s_mul_i32 s31, s30, s28
	s_sub_i32 s7, s7, s31
	s_add_i32 s51, s30, 1
	s_sub_i32 s31, s7, s28
	s_cmp_ge_u32 s7, s28
	s_cselect_b32 s30, s51, s30
	s_cselect_b32 s7, s31, s7
	s_add_i32 s31, s30, 1
	s_cmp_ge_u32 s7, s28
	s_cselect_b32 s7, s31, s30
	s_xor_b32 s7, s7, s29
	s_sub_i32 s51, s7, s29
	s_mul_i32 s7, s51, s23
	s_sub_i32 s6, s6, s7
	s_add_i32 s52, s6, s22
